# P6 sample attention: the 8 q-slab loads of a unit issued together (one wait instead of two), on top of the P2b epilogue ring
# baseline (speedup 1.0000x reference)
.LBB0_846:
	s_or_b64 exec, exec, s[58:59]
	s_waitcnt lgkmcnt(0)
	s_barrier
	ds_read_b32 v0, v92
	s_movk_i32 s40, 0x1ff
	s_mov_b64 s[58:59], -1
	s_waitcnt lgkmcnt(0)
	v_cmp_lt_i32_e32 vcc, s40, v0
	v_readfirstlane_b32 s66, v0
	s_cbranch_vccnz .LBB0_843
	s_mov_b32 s40, 3
	s_ashr_i32 s41, s40, 31
	s_ashr_i32 s58, s66, 2
	s_lshl_b64 s[40:41], s[40:41], 3
	s_add_u32 s40, s0, s40
	s_addc_u32 s41, s1, s41
	s_load_dwordx2 s[64:65], s[40:41], 0x0
	s_lshl_b32 s40, s66, 9
	s_and_b32 s48, s40, 0x600
	s_mov_b32 s40, 4
	s_ashr_i32 s41, s40, 31
	s_lshl_b64 s[40:41], s[40:41], 3
	s_add_u32 s40, s0, s40
	s_addc_u32 s41, s1, s41
	s_load_dwordx2 s[60:61], s[40:41], 0x0
	s_and_b64 vcc, exec, s[14:15]
	s_lshl_b32 s67, s58, 3
	s_cbranch_vccnz .LBB0_849
	v_add_u32_e32 v0, s67, v85
	v_ashrrev_i32_e32 v1, 31, v0
	v_lshlrev_b64 v[0:1], 12, v[0:1]
	v_lshl_add_u64 v[0:1], s[50:51], 0, v[0:1]
	s_lshl_b32 s40, s48, 1
	s_mov_b32 s41, s49
	v_lshl_add_u64 v[0:1], v[0:1], 0, s[40:41]
	v_mov_b32_e32 v73, v65
	v_lshl_add_u64 v[8:9], v[0:1], 0, v[72:73]
	s_mov_b32 s40, 0x400000
	v_add_co_u32_e32 v4, vcc, s40, v8
	s_mov_b32 s40, 0x800000
	s_nop 0
	v_addc_co_u32_e32 v5, vcc, 0, v9, vcc
	v_add_co_u32_e32 v10, vcc, s40, v8
	s_mov_b32 s40, 0xc00000
	s_nop 0
	v_addc_co_u32_e32 v11, vcc, 0, v9, vcc
	flat_load_dwordx4 v[12:15], v[10:11]
	v_add_co_u32_e32 v10, vcc, s40, v8
	s_mov_b32 s40, 0x1000000
	s_nop 0
	v_addc_co_u32_e32 v11, vcc, 0, v9, vcc
	flat_load_dwordx4 v[16:19], v[10:11]
	v_add_co_u32_e32 v10, vcc, s40, v8
	flat_load_dwordx4 v[0:3], v[8:9]
	s_nop 0
	v_addc_co_u32_e32 v11, vcc, 0, v9, vcc
	s_mov_b32 s40, 0x1400000
	flat_load_dwordx4 v[4:7], v[4:5]
	flat_load_dwordx4 v[20:23], v[10:11]
	v_add_co_u32_e32 v10, vcc, s40, v8
	s_mov_b32 s40, 0x1800000
	s_nop 0
	v_addc_co_u32_e32 v11, vcc, 0, v9, vcc
	flat_load_dwordx4 v[24:27], v[10:11]
	v_add_co_u32_e32 v10, vcc, s40, v8
	s_mov_b32 s40, 0x1c00000
	s_nop 0
	v_addc_co_u32_e32 v11, vcc, 0, v9, vcc
	v_add_co_u32_e32 v8, vcc, s40, v8
	flat_load_dwordx4 v[28:31], v[10:11]
	s_nop 0
	v_addc_co_u32_e32 v9, vcc, 0, v9, vcc
	flat_load_dwordx4 v[8:11], v[8:9]
	s_waitcnt vmcnt(0) lgkmcnt(0)
	v_lshlrev_b32_e32 v40, 16, v12
	v_lshlrev_b32_e32 v32, 16, v0
	v_and_b32_e32 v33, 0xffff0000, v0
	v_lshlrev_b32_e32 v0, 16, v1
	v_and_b32_e32 v1, 0xffff0000, v1
	v_lshlrev_b32_e32 v34, 16, v2
	v_and_b32_e32 v35, 0xffff0000, v2
	v_lshlrev_b32_e32 v2, 16, v3
	v_and_b32_e32 v3, 0xffff0000, v3
	v_pk_add_f32 v[0:1], v[0:1], 0 op_sel_hi:[1,0]
	v_pk_add_f32 v[32:33], v[32:33], 0 op_sel_hi:[1,0]
	v_pk_add_f32 v[2:3], v[2:3], 0 op_sel_hi:[1,0]
	v_pk_add_f32 v[34:35], v[34:35], 0 op_sel_hi:[1,0]
	v_lshlrev_b32_e32 v36, 16, v4
	v_and_b32_e32 v37, 0xffff0000, v4
	v_lshlrev_b32_e32 v4, 16, v5
	v_and_b32_e32 v5, 0xffff0000, v5
	v_lshlrev_b32_e32 v38, 16, v6
	v_and_b32_e32 v39, 0xffff0000, v6
	v_lshlrev_b32_e32 v6, 16, v7
	v_and_b32_e32 v7, 0xffff0000, v7
	v_and_b32_e32 v41, 0xffff0000, v12
	v_lshlrev_b32_e32 v12, 16, v13
	v_and_b32_e32 v13, 0xffff0000, v13
	v_lshlrev_b32_e32 v42, 16, v14
	v_and_b32_e32 v43, 0xffff0000, v14
	v_lshlrev_b32_e32 v14, 16, v15
	v_and_b32_e32 v15, 0xffff0000, v15
	v_pk_add_f32 v[32:33], v[32:33], v[36:37]
	v_pk_add_f32 v[0:1], v[0:1], v[4:5]
	v_pk_add_f32 v[4:5], v[34:35], v[38:39]
	v_pk_add_f32 v[2:3], v[2:3], v[6:7]
	v_lshlrev_b32_e32 v44, 16, v16
	v_and_b32_e32 v45, 0xffff0000, v16
	v_pk_add_f32 v[0:1], v[0:1], v[12:13]
	v_pk_add_f32 v[6:7], v[32:33], v[40:41]
	v_pk_add_f32 v[2:3], v[2:3], v[14:15]
	v_pk_add_f32 v[4:5], v[4:5], v[42:43]
	v_lshlrev_b32_e32 v12, 16, v17
	v_and_b32_e32 v13, 0xffff0000, v17
	v_lshlrev_b32_e32 v14, 16, v18
	v_and_b32_e32 v15, 0xffff0000, v18
	v_lshlrev_b32_e32 v16, 16, v19
	v_and_b32_e32 v17, 0xffff0000, v19
	v_pk_add_f32 v[6:7], v[6:7], v[44:45]
	v_pk_add_f32 v[0:1], v[0:1], v[12:13]
	v_pk_add_f32 v[4:5], v[4:5], v[14:15]
	v_pk_add_f32 v[2:3], v[2:3], v[16:17]
	s_waitcnt vmcnt(0) lgkmcnt(0)
	v_lshlrev_b32_e32 v12, 16, v20
	v_and_b32_e32 v13, 0xffff0000, v20
	v_lshlrev_b32_e32 v14, 16, v21
	v_and_b32_e32 v15, 0xffff0000, v21
	v_lshlrev_b32_e32 v18, 16, v23
	v_and_b32_e32 v19, 0xffff0000, v23
	v_lshlrev_b32_e32 v16, 16, v22
	v_and_b32_e32 v17, 0xffff0000, v22
	v_pk_add_f32 v[0:1], v[0:1], v[14:15]
	v_pk_add_f32 v[6:7], v[6:7], v[12:13]
	v_pk_add_f32 v[2:3], v[2:3], v[18:19]
	v_lshlrev_b32_e32 v12, 16, v24
	v_and_b32_e32 v13, 0xffff0000, v24
	v_lshlrev_b32_e32 v14, 16, v25
	v_and_b32_e32 v15, 0xffff0000, v25
	v_lshlrev_b32_e32 v18, 16, v27
	v_and_b32_e32 v19, 0xffff0000, v27
	v_pk_add_f32 v[4:5], v[4:5], v[16:17]
	v_lshlrev_b32_e32 v16, 16, v26
	v_and_b32_e32 v17, 0xffff0000, v26
	v_pk_add_f32 v[6:7], v[6:7], v[12:13]
	v_pk_add_f32 v[0:1], v[0:1], v[14:15]
	v_pk_add_f32 v[12:13], v[2:3], v[18:19]
	v_lshlrev_b32_e32 v2, 16, v29
	v_and_b32_e32 v3, 0xffff0000, v29
	v_lshlrev_b32_e32 v18, 16, v31
	v_and_b32_e32 v19, 0xffff0000, v31
	v_pk_add_f32 v[4:5], v[4:5], v[16:17]
	v_lshlrev_b32_e32 v14, 16, v28
	v_and_b32_e32 v15, 0xffff0000, v28
	v_lshlrev_b32_e32 v16, 16, v30
	v_and_b32_e32 v17, 0xffff0000, v30
	v_pk_add_f32 v[2:3], v[0:1], v[2:3]
	v_pk_add_f32 v[0:1], v[12:13], v[18:19]
	v_lshlrev_b32_e32 v12, 16, v8
	v_and_b32_e32 v13, 0xffff0000, v8
	v_lshlrev_b32_e32 v8, 16, v9
	v_and_b32_e32 v9, 0xffff0000, v9
	v_pk_add_f32 v[6:7], v[6:7], v[14:15]
	v_pk_add_f32 v[4:5], v[4:5], v[16:17]
	v_lshlrev_b32_e32 v14, 16, v10
	v_and_b32_e32 v15, 0xffff0000, v10
	v_lshlrev_b32_e32 v10, 16, v11
	v_and_b32_e32 v11, 0xffff0000, v11
	v_pk_add_f32 v[2:3], v[2:3], v[8:9]
	v_pk_add_f32 v[6:7], v[6:7], v[12:13]
	v_pk_add_f32 v[4:5], v[4:5], v[14:15]
	v_pk_add_f32 v[0:1], v[0:1], v[10:11]
	v_pk_mul_f32 v[2:3], v[2:3], s[54:55] op_sel_hi:[1,0]
	v_pk_mul_f32 v[6:7], v[6:7], s[54:55] op_sel_hi:[1,0]
	v_pk_mul_f32 v[8:9], v[0:1], s[54:55] op_sel_hi:[1,0]
	v_pk_mul_f32 v[4:5], v[4:5], s[54:55] op_sel_hi:[1,0]
	v_cvt_pk_bf16_f32 v0, v6, v7
	v_cvt_pk_bf16_f32 v1, v2, v3
	s_nop 0
	v_cvt_pk_bf16_f32 v2, v4, v5
	v_cvt_pk_bf16_f32 v3, v8, v9
	ds_write_b128 v86, v[0:3] offset:9472
	s_waitcnt lgkmcnt(0)
	s_barrier
